# speedup vs baseline: 1.0111x; 1.0082x over previous
; #define LAS __attribute__((address_space(3)))
; __device__ __forceinline__ void transpose_item(const float* W, int N, bf16* WT, int ldk, int k0, int n0, int row_base, LAS float* scr, int lane) {
; #pragma unroll
;     for (int i = 0; i < 32; ++i) { const int kk = 2 * i + (lane >> 5); scr[kk * 33 + (lane & 31)] = W[(size_t)(k0 + kk) * N + n0 + (lane & 31)]; }
; __device__ __forceinline__ void ffn_transpose_items(const float* Wg, const float* Wu, const float* Wd, bf16* WGU, bf16* WD, LAS float* scr, int lane, int first, int stride, int nlimit  ) {
;     constexpr int I1 = (DM / 64) * (FF / 32);
;     for (int it = first; it < nlimit; it += stride) {
;         int r = it;
;         if (r < 2 * I1) { const bool up = r >= I1; if (up) r -= I1; const int kb = r / (FF / 32), nb = r % (FF / 32), n0 = 32 * nb;
;             transpose_item(up ? Wu : Wg, FF, WGU, DM, 64 * kb, n0, 256 * (n0 >> 7) + (n0 & 127) + (up ? 128 : 0), scr, lane); }
.LBB0_5:
	s_add_i32 s16, s19, 0xffffea80
	s_cmpk_gt_i32 s19, 0x157f
	s_cselect_b32 s26, s16, s19
	s_mul_hi_i32 s16, s26, 0x2fa0be83
	s_cselect_b32 s24, 0x80, 0
	s_cselect_b32 s17, s7, s5
	s_cselect_b32 s25, s6, s4
	s_lshr_b32 s27, s16, 31
	s_ashr_i32 s16, s16, 5
	s_add_i32 s16, s16, s27
	s_mul_i32 s27, s16, 0xac
	s_sub_i32 s27, s26, s27
	s_lshl_b32 s26, s27, 5
	s_lshl_b32 s27, s27, 6
	s_and_b32 s29, s26, 0x60
	s_and_b32 s28, s27, 0xffffff00
	s_ashr_i32 s27, s26, 31
	s_or_b32 s24, s29, s24
	s_lshl_b32 s16, s16, 6
	s_lshl_b64 s[26:27], s[26:27], 2
	s_or_b32 s24, s24, s28
	s_add_u32 s26, s25, s26
	s_addc_u32 s27, s17, s27
	v_or_b32_e32 v52, s16, v1
	v_or_b32_e32 v62, s16, v10
	v_or_b32_e32 v64, s16, v11
	v_or_b32_e32 v66, s16, v12
	v_or_b32_e32 v68, s16, v13
	v_or_b32_e32 v70, s16, v14
	v_or_b32_e32 v72, s16, v15
	v_or_b32_e32 v74, s16, v16
	v_or_b32_e32 v76, s16, v17
	v_or_b32_e32 v78, s16, v18
	v_or_b32_e32 v80, s16, v19
	v_lshl_add_u64 v[50:51], s[26:27], 0, v[2:3]
	v_or_b32_e32 v54, s16, v6
	v_or_b32_e32 v56, s16, v7
	v_or_b32_e32 v58, s16, v8
	v_or_b32_e32 v60, s16, v9
	v_or_b32_e32 v82, s16, v20
	v_or_b32_e32 v84, s16, v21
	v_or_b32_e32 v86, s16, v22
	v_or_b32_e32 v88, s16, v23
	v_or_b32_e32 v90, s16, v24
	v_or_b32_e32 v92, s16, v25
	v_or_b32_e32 v94, s16, v26
	v_or_b32_e32 v96, s16, v27
	v_or_b32_e32 v98, s16, v28
	v_or_b32_e32 v100, s16, v29
	v_or_b32_e32 v102, s16, v30
	v_or_b32_e32 v104, s16, v31
	v_or_b32_e32 v106, s16, v32
	v_or_b32_e32 v108, s16, v33
	v_or_b32_e32 v110, s16, v34
	v_or_b32_e32 v112, s16, v35
	v_or_b32_e32 v114, s16, v36
	v_mad_i64_i32 v[52:53], s[26:27], v52, s18, v[50:51]
	v_mad_i64_i32 v[62:63], s[26:27], v62, s18, v[50:51]
	v_mad_i64_i32 v[64:65], s[26:27], v64, s18, v[50:51]
	v_mad_i64_i32 v[66:67], s[26:27], v66, s18, v[50:51]
	v_mad_i64_i32 v[68:69], s[26:27], v68, s18, v[50:51]
	v_mad_i64_i32 v[70:71], s[26:27], v70, s18, v[50:51]
	v_mad_i64_i32 v[72:73], s[26:27], v72, s18, v[50:51]
	v_mad_i64_i32 v[74:75], s[26:27], v74, s18, v[50:51]
	v_mad_i64_i32 v[76:77], s[26:27], v76, s18, v[50:51]
	v_mad_i64_i32 v[78:79], s[26:27], v78, s18, v[50:51]
	v_mad_i64_i32 v[80:81], s[26:27], v80, s18, v[50:51]
	v_mad_i64_i32 v[54:55], s[26:27], v54, s18, v[50:51]
	v_mad_i64_i32 v[56:57], s[26:27], v56, s18, v[50:51]
	v_mad_i64_i32 v[58:59], s[26:27], v58, s18, v[50:51]
	v_mad_i64_i32 v[60:61], s[26:27], v60, s18, v[50:51]
	v_mad_i64_i32 v[82:83], s[26:27], v82, s18, v[50:51]
	v_mad_i64_i32 v[84:85], s[26:27], v84, s18, v[50:51]
	v_mad_i64_i32 v[86:87], s[26:27], v86, s18, v[50:51]
	v_mad_i64_i32 v[88:89], s[26:27], v88, s18, v[50:51]
	v_mad_i64_i32 v[90:91], s[26:27], v90, s18, v[50:51]
	v_mad_i64_i32 v[92:93], s[26:27], v92, s18, v[50:51]
	v_mad_i64_i32 v[94:95], s[26:27], v94, s18, v[50:51]
	v_mad_i64_i32 v[96:97], s[26:27], v96, s18, v[50:51]
	v_mad_i64_i32 v[98:99], s[26:27], v98, s18, v[50:51]
	v_mad_i64_i32 v[100:101], s[26:27], v100, s18, v[50:51]
	v_mad_i64_i32 v[102:103], s[26:27], v102, s18, v[50:51]
	v_mad_i64_i32 v[104:105], s[26:27], v104, s18, v[50:51]
	v_mad_i64_i32 v[106:107], s[26:27], v106, s18, v[50:51]
	v_mad_i64_i32 v[108:109], s[26:27], v108, s18, v[50:51]
	v_mad_i64_i32 v[110:111], s[26:27], v110, s18, v[50:51]
	v_mad_i64_i32 v[112:113], s[26:27], v112, s18, v[50:51]
	v_mad_i64_i32 v[50:51], s[26:27], v114, s18, v[50:51]
	global_load_dword v114, v[52:53], off
	global_load_dword v115, v[54:55], off
	global_load_dword v116, v[56:57], off
	global_load_dword v117, v[58:59], off
	global_load_dword v118, v[60:61], off
	global_load_dword v119, v[62:63], off
	global_load_dword v120, v[64:65], off
	global_load_dword v121, v[66:67], off
	global_load_dword v122, v[68:69], off
	global_load_dword v123, v[70:71], off
	global_load_dword v124, v[72:73], off
	global_load_dword v125, v[74:75], off
	global_load_dword v62, v[76:77], off
	global_load_dword v63, v[78:79], off
	global_load_dword v64, v[80:81], off
	global_load_dword v65, v[82:83], off
	global_load_dword v66, v[84:85], off
	global_load_dword v67, v[86:87], off
	global_load_dword v68, v[88:89], off
	global_load_dword v69, v[90:91], off
	global_load_dword v70, v[92:93], off
	global_load_dword v71, v[94:95], off
	global_load_dword v72, v[96:97], off
	global_load_dword v73, v[98:99], off
	global_load_dword v74, v[100:101], off
	global_load_dword v75, v[102:103], off
	global_load_dword v126, v[104:105], off
	global_load_dword v76, v[106:107], off
	global_load_dword v77, v[108:109], off
	global_load_dword v78, v[110:111], off
	global_load_dword v79, v[112:113], off
	global_load_dword v80, v[50:51], off
	v_or_b32_e32 v50, s24, v37
	v_or_b32_e32 v52, s24, v39
	s_ashr_i32 s17, s16, 31
	v_ashrrev_i32_e32 v51, 31, v50
	s_waitcnt vmcnt(30)
; #define LAS __attribute__((address_space(3)))
; __device__ __forceinline__ unsigned pk2(float lo, float hi) { return pg8::cvt_pk_bf16(lo, hi); }
; __device__ __forceinline__ void transpose_item(const float* W, int N, bf16* WT, int ldk, int k0, int n0, int row_base, LAS float* scr, int lane) {
;     ...
;     for (int i = 0; i < 32; ++i) { const int kk = 2 * i + (lane >> 5); scr[kk * 33 + (lane & 31)] = W[(size_t)(k0 + kk) * N + n0 + (lane & 31)]; }
;     asm volatile("s_waitcnt lgkmcnt(0)" ::: "memory");
;     const int c = lane & 7;
; #pragma unroll
;     for (int j = 0; j < 4; ++j) { const int n = (lane >> 3) + 8 * j; const LAS float* s = scr + (8 * c) * 33 + n;
;         u32x4 o; o.x = pk2(s[0 * 33], s[1 * 33]); o.y = pk2(s[2 * 33], s[3 * 33]); o.z = pk2(s[4 * 33], s[5 * 33]); o.w = pk2(s[6 * 33], s[7 * 33]);
;         *(u32x4*)(WT + (size_t)(row_base + n) * ldk + k0 + 8 * c) = o; }
;     asm volatile("s_waitcnt lgkmcnt(0)" ::: "memory");
	ds_write2_b32 v42, v114, v115 offset1:66
	s_waitcnt vmcnt(28)
	ds_write2_b32 v42, v116, v117 offset0:132 offset1:198
	s_waitcnt vmcnt(26)
	ds_write2_b32 v43, v118, v119 offset0:8 offset1:74
	s_waitcnt vmcnt(24)
	ds_write2_b32 v43, v120, v121 offset0:140 offset1:206
	s_waitcnt vmcnt(22)
	ds_write2_b32 v44, v122, v123 offset0:16 offset1:82
	s_waitcnt vmcnt(20)
	ds_write2_b32 v44, v124, v125 offset0:148 offset1:214
	s_waitcnt vmcnt(18)
	ds_write2_b32 v45, v62, v63 offset0:24 offset1:90
	s_waitcnt vmcnt(16)
	ds_write2_b32 v45, v64, v65 offset0:156 offset1:222
	s_waitcnt vmcnt(14)
	ds_write2_b32 v46, v66, v67 offset0:32 offset1:98
	s_waitcnt vmcnt(12)
	ds_write2_b32 v46, v68, v69 offset0:164 offset1:230
	s_waitcnt vmcnt(10)
	ds_write2_b32 v47, v70, v71 offset0:40 offset1:106
	s_waitcnt vmcnt(8)
	ds_write2_b32 v47, v72, v73 offset0:172 offset1:238
	s_waitcnt vmcnt(6)
	ds_write2_b32 v48, v74, v75 offset0:48 offset1:114
	s_waitcnt vmcnt(4)
	ds_write2_b32 v48, v126, v76 offset0:180 offset1:246
	s_waitcnt vmcnt(2)
	ds_write2_b32 v49, v77, v78 offset0:56 offset1:122
	s_waitcnt vmcnt(0)
	ds_write2_b32 v49, v79, v80 offset0:188 offset1:254
	v_ashrrev_i32_e32 v53, 31, v52
	v_lshl_add_u64 v[56:57], s[16:17], 1, v[4:5]
	v_lshlrev_b64 v[50:51], 12, v[50:51]
	v_lshlrev_b64 v[52:53], 12, v[52:53]
	s_waitcnt lgkmcnt(0)
	ds_read2_b32 v[62:63], v38 offset1:33
	ds_read2_b32 v[64:65], v38 offset0:66 offset1:99
	ds_read2_b32 v[66:67], v38 offset0:132 offset1:165
	ds_read2_b32 v[68:69], v38 offset0:198 offset1:231
	ds_read2_b32 v[70:71], v38 offset0:8 offset1:41
	ds_read2_b32 v[72:73], v38 offset0:74 offset1:107
	ds_read2_b32 v[74:75], v38 offset0:140 offset1:173
	ds_read2_b32 v[76:77], v38 offset0:206 offset1:239
	v_lshl_add_u64 v[58:59], v[56:57], 0, v[50:51]
	v_lshl_add_u64 v[60:61], v[56:57], 0, v[52:53]
	v_or_b32_e32 v54, s24, v40
	v_ashrrev_i32_e32 v55, 31, v54
	v_lshlrev_b64 v[54:55], 12, v[54:55]
	v_lshl_add_u64 v[54:55], v[56:57], 0, v[54:55]
	v_or_b32_e32 v50, s24, v41
	v_ashrrev_i32_e32 v51, 31, v50
	v_lshlrev_b64 v[50:51], 12, v[50:51]
	v_lshl_add_u64 v[56:57], v[56:57], 0, v[50:51]
	ds_read2_b32 v[78:79], v38 offset0:16 offset1:49
	ds_read2_b32 v[114:115], v38 offset0:82 offset1:115
	ds_read2_b32 v[116:117], v38 offset0:148 offset1:181
	ds_read2_b32 v[118:119], v38 offset0:214 offset1:247
	ds_read2_b32 v[120:121], v38 offset0:24 offset1:57
	ds_read2_b32 v[122:123], v38 offset0:90 offset1:123
	ds_read2_b32 v[124:125], v38 offset0:156 offset1:189
	ds_read2_b32 v[52:53], v38 offset0:222 offset1:255
	s_add_i32 s19, s19, s36
	s_cmpk_lt_i32 s19, 0x2b00
	s_waitcnt lgkmcnt(8)
	v_cvt_pk_bf16_f32 v62, v62, v63
	v_cvt_pk_bf16_f32 v63, v64, v65
	v_cvt_pk_bf16_f32 v64, v66, v67
	v_cvt_pk_bf16_f32 v65, v68, v69
	v_cvt_pk_bf16_f32 v66, v70, v71
	v_cvt_pk_bf16_f32 v67, v72, v73
	global_store_dwordx4 v[58:59], v[62:65], off
	v_cvt_pk_bf16_f32 v68, v74, v75
	v_cvt_pk_bf16_f32 v69, v76, v77
	s_waitcnt lgkmcnt(0)
	v_cvt_pk_bf16_f32 v70, v78, v79
	global_store_dwordx4 v[60:61], v[66:69], off
	v_cvt_pk_bf16_f32 v71, v114, v115
	v_cvt_pk_bf16_f32 v72, v116, v117
	v_cvt_pk_bf16_f32 v73, v118, v119
	v_cvt_pk_bf16_f32 v74, v120, v121
	v_cvt_pk_bf16_f32 v75, v122, v123
	global_store_dwordx4 v[54:55], v[70:73], off
	v_cvt_pk_bf16_f32 v76, v124, v125
	v_cvt_pk_bf16_f32 v77, v52, v53
	s_nop 0
	global_store_dwordx4 v[56:57], v[74:77], off
	s_waitcnt lgkmcnt(0)
	s_cbranch_scc1 .LBB0_5

; __device__ __forceinline__ unsigned f2bf(float f) { unsigned u = __builtin_bit_cast(unsigned, f); return (u + 0x7fffu + ((u >> 16) & 1u)) >> 16; }
; __global__ void __launch_bounds__(NTHREADS, 2) fwd_kernel(Args args) {
;     ...
;         for (int i = gt; i < LN * LK; i += NT) { const int n = i / LK, k = i % LK, type = n >> 10, nn = n & 1023; float v = 0.f;
;             if (type == 0) { if (k < 64) v = ap->in[I_WDU][k * RW + nn]; } else if (type == 1) { if (k >= 64 && k < 128) v = ap->in[I_WAU][(k - 64) * RW + nn]; } else { if (k >= 128 && k < 288) v = ap->in[I_WGU][(k - 128) * RW + nn]; }
;             WLORA[i] = (bf16)f2bf(v); }
.LBB0_19:
	s_or_b64 exec, exec, s[6:7]
	s_mov_b32 s5, 0x120000
	v_cmp_gt_i32_e32 vcc, s5, v6
	s_and_saveexec_b64 s[6:7], vcc
	s_cbranch_execz .LBB0_38
	s_load_dwordx2 s[16:17], s[14:15], 0x90
	s_load_dwordx2 s[18:19], s[14:15], 0x88
	s_load_dwordx2 s[24:25], s[14:15], 0x78
	s_waitcnt lgkmcnt(0)
	s_add_u32 s26, s12, 0x6280000
	s_addc_u32 s27, s13, 0
	v_lshlrev_b32_e32 v1, 10, v6
	s_lshl_b32 s5, s4, 10
	s_mov_b64 s[28:29], 0
	s_mov_b32 s33, 0x2aaaaaab
	s_movk_i32 s35, 0x3ff
	s_movk_i32 s37, 0x400
	s_movk_i32 s42, 0xa0
	s_mov_b32 s43, 0xfffe0000
	v_mov_b32_e32 v3, 0
	s_mov_b32 s52, 0xffff0000
	s_movk_i32 s53, 0x7fff
	s_mov_b32 s54, 0x11ffff
	s_branch .LBB0_22

; __device__ __forceinline__ unsigned f2bf(float f) { unsigned u = __builtin_bit_cast(unsigned, f); return (u + 0x7fffu + ((u >> 16) & 1u)) >> 16; }
; __global__ void __launch_bounds__(NTHREADS, 2) fwd_kernel(Args args) {
;     ...
;         for (int i = gt; i < LN * LK; i += NT) { const int n = i / LK, k = i % LK, type = n >> 10, nn = n & 1023; float v = 0.f;
;             if (type == 0) { if (k < 64) v = ap->in[I_WDU][k * RW + nn]; } else if (type == 1) { if (k >= 64 && k < 128) v = ap->in[I_WAU][(k - 64) * RW + nn]; } else { if (k >= 128 && k < 288) v = ap->in[I_WGU][(k - 128) * RW + nn]; }
;             WLORA[i] = (bf16)f2bf(v); }
.LBB0_37:
	v_lshl_add_u64 v[4:5], v[4:5], 2, v[8:9]
	global_load_dword v2, v[4:5], off
	s_branch .LBB0_21
